# SwiGLU epilogue: 8 row-ssq loads hoisted and issued together, counted vmcnt(7) per group instead of load+vmcnt(0) each
# speedup vs baseline: 1.0076x; 1.0048x over previous
.LBB0_958:
	v_lshl_add_u32 v142, s22, 8, v144
	v_ashrrev_i32_e32 v143, 31, v142
	v_lshl_add_u64 v[200:201], v[142:143], 3, s[80:81]
	global_load_dwordx2 v[202:203], v[200:201], off
	global_load_dwordx2 v[204:205], v[200:201], off offset:128
	global_load_dwordx2 v[206:207], v[200:201], off offset:256
	global_load_dwordx2 v[208:209], v[200:201], off offset:384
	global_load_dwordx2 v[210:211], v[200:201], off offset:1024
	global_load_dwordx2 v[212:213], v[200:201], off offset:1152
	global_load_dwordx2 v[214:215], v[200:201], off offset:1280
	global_load_dwordx2 v[216:217], v[200:201], off offset:1408
	s_lshl_b32 s22, s14, 7
	s_ashr_i32 s23, s22, 31
	s_lshl_b64 s[22:23], s[22:23], 1
	s_andn2_b64 vcc, exec, s[2:3]
	s_waitcnt vmcnt(7)
	v_ffbh_u32_e32 v143, v203
	v_min_u32_e32 v143, 32, v143
	v_lshlrev_b64 v[148:149], v143, v[202:203]
	v_min_u32_e32 v147, 1, v148
	v_or_b32_e32 v147, v149, v147
	v_cvt_f32_u32_e32 v147, v147
	v_sub_u32_e32 v143, 32, v143
	v_ldexp_f32 v143, v147, v143
	v_mul_f32_e32 v143, 0x37800000, v143
	v_fmamk_f32 v143, v143, 0x3a800000, v195
	v_rsq_f32_e32 v148, v143
	s_nop 0
	v_pk_mul_f32 v[126:127], v[126:127], v[148:149] op_sel_hi:[1,0]
	s_nop 0
	v_mul_f32_e32 v143, 0xbfb8aa3b, v126
	v_exp_f32_e32 v143, v143
	v_pk_mul_f32 v[118:119], v[118:119], v[148:149] op_sel_hi:[1,0]
	v_pk_mul_f32 v[120:121], v[120:121], v[148:149] op_sel_hi:[1,0]
	v_pk_mul_f32 v[122:123], v[122:123], v[148:149] op_sel_hi:[1,0]
	v_add_f32_e32 v143, 1.0, v143
	v_rcp_f32_e32 v150, v143
	v_mul_f32_e32 v143, 0xbfb8aa3b, v127
	v_exp_f32_e32 v143, v143
	v_pk_mul_f32 v[114:115], v[114:115], v[148:149] op_sel_hi:[1,0]
	v_pk_mul_f32 v[116:117], v[116:117], v[148:149] op_sel_hi:[1,0]
	v_add_f32_e32 v143, 1.0, v143
	v_rcp_f32_e32 v151, v143
	s_nop 0
	v_pk_mul_f32 v[126:127], v[126:127], v[150:151]
	s_nop 0
	v_pk_mul_f32 v[118:119], v[118:119], v[126:127]
	v_pk_mul_f32 v[126:127], v[128:129], v[148:149] op_sel_hi:[1,0]
	s_nop 0
	v_mul_f32_e32 v128, 0xbfb8aa3b, v126
	v_mul_f32_e32 v129, 0xbfb8aa3b, v127
	v_exp_f32_e32 v128, v128
	v_exp_f32_e32 v129, v129
	v_add_f32_e32 v128, 1.0, v128
	v_add_f32_e32 v129, 1.0, v129
	v_rcp_f32_e32 v128, v128
	v_rcp_f32_e32 v129, v129
	s_nop 0
	v_pk_mul_f32 v[126:127], v[126:127], v[128:129]
	s_nop 0
	v_pk_mul_f32 v[120:121], v[120:121], v[126:127]
	v_mul_f32_e32 v126, 0xbfb8aa3b, v122
	v_mul_f32_e32 v127, 0xbfb8aa3b, v123
	v_exp_f32_e32 v126, v126
	v_exp_f32_e32 v127, v127
	v_add_f32_e32 v126, 1.0, v126
	v_add_f32_e32 v127, 1.0, v127
	v_rcp_f32_e32 v126, v126
	v_rcp_f32_e32 v127, v127
	s_nop 0
	v_pk_mul_f32 v[122:123], v[122:123], v[126:127]
	s_nop 0
	v_pk_mul_f32 v[122:123], v[114:115], v[122:123]
	v_pk_mul_f32 v[114:115], v[124:125], v[148:149] op_sel_hi:[1,0]
	s_nop 0
	v_mul_f32_e32 v124, 0xbfb8aa3b, v114
	v_mul_f32_e32 v125, 0xbfb8aa3b, v115
	v_exp_f32_e32 v124, v124
	v_exp_f32_e32 v125, v125
	v_add_f32_e32 v124, 1.0, v124
	v_add_f32_e32 v125, 1.0, v125
	v_rcp_f32_e32 v124, v124
	v_rcp_f32_e32 v125, v125
	s_nop 0
	v_pk_mul_f32 v[114:115], v[114:115], v[124:125]
	s_nop 0
	v_pk_mul_f32 v[124:125], v[116:117], v[114:115]
	v_cvt_pk_bf16_f32 v114, v118, v119
	v_mov_b64_e32 v[118:119], s[56:57]
	v_cvt_pk_bf16_f32 v115, v120, v121
	v_mad_i64_i32 v[120:121], s[12:13], v142, s83, v[118:119]
	v_lshl_add_u64 v[120:121], v[120:121], 0, s[22:23]
	v_lshl_add_u64 v[120:121], v[120:121], 0, s[90:91]
	v_cvt_pk_bf16_f32 v116, v122, v123
	v_cvt_pk_bf16_f32 v117, v124, v125
	v_lshl_add_u64 v[120:121], v[120:121], 0, v[0:1]
	global_store_dwordx4 v[120:121], v[114:117], off
	s_nop 1
	v_or_b32_e32 v114, 16, v142
	v_ashrrev_i32_e32 v115, 31, v114
	s_waitcnt vmcnt(7)
	v_ffbh_u32_e32 v115, v205
	v_min_u32_e32 v115, 32, v115
	v_lshlrev_b64 v[116:117], v115, v[204:205]
	v_min_u32_e32 v116, 1, v116
	v_or_b32_e32 v116, v117, v116
	v_cvt_f32_u32_e32 v116, v116
	v_sub_u32_e32 v115, 32, v115
	v_ldexp_f32 v115, v116, v115
	v_mul_f32_e32 v115, 0x37800000, v115
	v_fmamk_f32 v115, v115, 0x3a800000, v195
	v_rsq_f32_e32 v116, v115
	s_nop 0
	v_pk_mul_f32 v[110:111], v[110:111], v[116:117] op_sel_hi:[1,0]
	s_nop 0
	v_mul_f32_e32 v115, 0xbfb8aa3b, v110
	v_exp_f32_e32 v115, v115
	v_pk_mul_f32 v[102:103], v[102:103], v[116:117] op_sel_hi:[1,0]
	v_pk_mul_f32 v[104:105], v[104:105], v[116:117] op_sel_hi:[1,0]
	v_pk_mul_f32 v[106:107], v[106:107], v[116:117] op_sel_hi:[1,0]
	v_add_f32_e32 v115, 1.0, v115
	v_rcp_f32_e32 v120, v115
	v_mul_f32_e32 v115, 0xbfb8aa3b, v111
	v_exp_f32_e32 v115, v115
	v_pk_mul_f32 v[98:99], v[98:99], v[116:117] op_sel_hi:[1,0]
	v_pk_mul_f32 v[100:101], v[100:101], v[116:117] op_sel_hi:[1,0]
	v_add_f32_e32 v115, 1.0, v115
	v_rcp_f32_e32 v121, v115
	s_nop 0
	v_pk_mul_f32 v[110:111], v[110:111], v[120:121]
	s_nop 0
	v_pk_mul_f32 v[102:103], v[102:103], v[110:111]
	v_pk_mul_f32 v[110:111], v[112:113], v[116:117] op_sel_hi:[1,0]
	s_nop 0
	v_mul_f32_e32 v112, 0xbfb8aa3b, v110
	v_mul_f32_e32 v113, 0xbfb8aa3b, v111
	v_exp_f32_e32 v112, v112
	v_exp_f32_e32 v113, v113
	v_add_f32_e32 v112, 1.0, v112
	v_add_f32_e32 v113, 1.0, v113
	v_rcp_f32_e32 v112, v112
	v_rcp_f32_e32 v113, v113
	s_nop 0
	v_pk_mul_f32 v[110:111], v[110:111], v[112:113]
	s_nop 0
	v_pk_mul_f32 v[104:105], v[104:105], v[110:111]
	v_mul_f32_e32 v110, 0xbfb8aa3b, v106
	v_mul_f32_e32 v111, 0xbfb8aa3b, v107
	v_exp_f32_e32 v110, v110
	v_exp_f32_e32 v111, v111
	v_add_f32_e32 v110, 1.0, v110
	v_add_f32_e32 v111, 1.0, v111
	v_rcp_f32_e32 v110, v110
	v_rcp_f32_e32 v111, v111
	s_nop 0
	v_pk_mul_f32 v[106:107], v[106:107], v[110:111]
	s_nop 0
	v_pk_mul_f32 v[106:107], v[98:99], v[106:107]
	v_pk_mul_f32 v[98:99], v[108:109], v[116:117] op_sel_hi:[1,0]
	s_nop 0
	v_mul_f32_e32 v108, 0xbfb8aa3b, v98
	v_mul_f32_e32 v109, 0xbfb8aa3b, v99
	v_exp_f32_e32 v108, v108
	v_exp_f32_e32 v109, v109
	v_add_f32_e32 v108, 1.0, v108
	v_add_f32_e32 v109, 1.0, v109
	v_rcp_f32_e32 v108, v108
	v_rcp_f32_e32 v109, v109
	s_nop 0
	v_pk_mul_f32 v[98:99], v[98:99], v[108:109]
	s_nop 0
	v_pk_mul_f32 v[108:109], v[100:101], v[98:99]
	v_cvt_pk_bf16_f32 v98, v102, v103
	v_mad_i64_i32 v[102:103], s[12:13], v114, s83, v[118:119]
	v_lshl_add_u64 v[102:103], v[102:103], 0, s[22:23]
	v_lshl_add_u64 v[102:103], v[102:103], 0, s[90:91]
	v_cvt_pk_bf16_f32 v99, v104, v105
	v_cvt_pk_bf16_f32 v100, v106, v107
	v_cvt_pk_bf16_f32 v101, v108, v109
	v_lshl_add_u64 v[102:103], v[102:103], 0, v[0:1]
	global_store_dwordx4 v[102:103], v[98:101], off
	s_nop 1
	v_or_b32_e32 v98, 32, v142
	v_ashrrev_i32_e32 v99, 31, v98
	s_waitcnt vmcnt(7)
	v_ffbh_u32_e32 v99, v207
	v_min_u32_e32 v99, 32, v99
	v_lshlrev_b64 v[100:101], v99, v[206:207]
	v_min_u32_e32 v100, 1, v100
	v_or_b32_e32 v100, v101, v100
	v_cvt_f32_u32_e32 v100, v100
	v_sub_u32_e32 v99, 32, v99
	v_ldexp_f32 v99, v100, v99
	v_mul_f32_e32 v99, 0x37800000, v99
	v_fmamk_f32 v99, v99, 0x3a800000, v195
	v_rsq_f32_e32 v100, v99
	s_nop 0
	v_pk_mul_f32 v[94:95], v[94:95], v[100:101] op_sel_hi:[1,0]
	s_nop 0
	v_mul_f32_e32 v99, 0xbfb8aa3b, v94
	v_exp_f32_e32 v99, v99
	v_pk_mul_f32 v[86:87], v[86:87], v[100:101] op_sel_hi:[1,0]
	v_pk_mul_f32 v[88:89], v[88:89], v[100:101] op_sel_hi:[1,0]
	v_pk_mul_f32 v[90:91], v[90:91], v[100:101] op_sel_hi:[1,0]
	v_add_f32_e32 v99, 1.0, v99
	v_rcp_f32_e32 v102, v99
	v_mul_f32_e32 v99, 0xbfb8aa3b, v95
	v_exp_f32_e32 v99, v99
	v_pk_mul_f32 v[82:83], v[82:83], v[100:101] op_sel_hi:[1,0]
	v_pk_mul_f32 v[84:85], v[84:85], v[100:101] op_sel_hi:[1,0]
	v_add_f32_e32 v99, 1.0, v99
	v_rcp_f32_e32 v103, v99
	s_nop 0
	v_pk_mul_f32 v[94:95], v[94:95], v[102:103]
	s_nop 0
	v_pk_mul_f32 v[86:87], v[86:87], v[94:95]
	v_pk_mul_f32 v[94:95], v[96:97], v[100:101] op_sel_hi:[1,0]
	s_nop 0
	v_mul_f32_e32 v96, 0xbfb8aa3b, v94
	v_mul_f32_e32 v97, 0xbfb8aa3b, v95
	v_exp_f32_e32 v96, v96
	v_exp_f32_e32 v97, v97
	v_add_f32_e32 v96, 1.0, v96
	v_add_f32_e32 v97, 1.0, v97
	v_rcp_f32_e32 v96, v96
	v_rcp_f32_e32 v97, v97
	s_nop 0
	v_pk_mul_f32 v[94:95], v[94:95], v[96:97]
	s_nop 0
	v_pk_mul_f32 v[88:89], v[88:89], v[94:95]
	v_mul_f32_e32 v94, 0xbfb8aa3b, v90
	v_mul_f32_e32 v95, 0xbfb8aa3b, v91
	v_exp_f32_e32 v94, v94
	v_exp_f32_e32 v95, v95
	v_add_f32_e32 v94, 1.0, v94
	v_add_f32_e32 v95, 1.0, v95
	v_rcp_f32_e32 v94, v94
	v_rcp_f32_e32 v95, v95
	s_nop 0
	v_pk_mul_f32 v[90:91], v[90:91], v[94:95]
	s_nop 0
	v_pk_mul_f32 v[90:91], v[82:83], v[90:91]
	v_pk_mul_f32 v[82:83], v[92:93], v[100:101] op_sel_hi:[1,0]
	s_nop 0
	v_mul_f32_e32 v92, 0xbfb8aa3b, v82
	v_mul_f32_e32 v93, 0xbfb8aa3b, v83
	v_exp_f32_e32 v92, v92
	v_exp_f32_e32 v93, v93
	v_add_f32_e32 v92, 1.0, v92
	v_add_f32_e32 v93, 1.0, v93
	v_rcp_f32_e32 v92, v92
	v_rcp_f32_e32 v93, v93
	s_nop 0
	v_pk_mul_f32 v[82:83], v[82:83], v[92:93]
	s_nop 0
	v_pk_mul_f32 v[92:93], v[84:85], v[82:83]
	v_cvt_pk_bf16_f32 v82, v86, v87
	v_mad_i64_i32 v[86:87], s[12:13], v98, s83, v[118:119]
	v_lshl_add_u64 v[86:87], v[86:87], 0, s[22:23]
	v_lshl_add_u64 v[86:87], v[86:87], 0, s[90:91]
	v_cvt_pk_bf16_f32 v83, v88, v89
	v_cvt_pk_bf16_f32 v84, v90, v91
	v_cvt_pk_bf16_f32 v85, v92, v93
	v_lshl_add_u64 v[86:87], v[86:87], 0, v[0:1]
	global_store_dwordx4 v[86:87], v[82:85], off
	s_nop 1
	v_or_b32_e32 v82, 48, v142
	v_ashrrev_i32_e32 v83, 31, v82
	s_waitcnt vmcnt(7)
	v_ffbh_u32_e32 v83, v209
	v_min_u32_e32 v83, 32, v83
	v_lshlrev_b64 v[84:85], v83, v[208:209]
	v_min_u32_e32 v84, 1, v84
	v_or_b32_e32 v84, v85, v84
	v_cvt_f32_u32_e32 v84, v84
	v_sub_u32_e32 v83, 32, v83
	v_ldexp_f32 v83, v84, v83
	v_mul_f32_e32 v83, 0x37800000, v83
	v_fmamk_f32 v83, v83, 0x3a800000, v195
	v_rsq_f32_e32 v84, v83
	s_nop 0
	v_pk_mul_f32 v[78:79], v[78:79], v[84:85] op_sel_hi:[1,0]
	s_nop 0
	v_mul_f32_e32 v83, 0xbfb8aa3b, v78
	v_exp_f32_e32 v83, v83
	v_pk_mul_f32 v[70:71], v[70:71], v[84:85] op_sel_hi:[1,0]
	v_pk_mul_f32 v[72:73], v[72:73], v[84:85] op_sel_hi:[1,0]
	v_pk_mul_f32 v[74:75], v[74:75], v[84:85] op_sel_hi:[1,0]
	v_add_f32_e32 v83, 1.0, v83
	v_rcp_f32_e32 v86, v83
	v_mul_f32_e32 v83, 0xbfb8aa3b, v79
	v_exp_f32_e32 v83, v83
	v_pk_mul_f32 v[66:67], v[66:67], v[84:85] op_sel_hi:[1,0]
	v_pk_mul_f32 v[68:69], v[68:69], v[84:85] op_sel_hi:[1,0]
	v_add_f32_e32 v83, 1.0, v83
	v_rcp_f32_e32 v87, v83
	s_nop 0
	v_pk_mul_f32 v[78:79], v[78:79], v[86:87]
	s_nop 0
	v_pk_mul_f32 v[70:71], v[70:71], v[78:79]
	v_pk_mul_f32 v[78:79], v[80:81], v[84:85] op_sel_hi:[1,0]
	s_nop 0
	v_mul_f32_e32 v80, 0xbfb8aa3b, v78
	v_mul_f32_e32 v81, 0xbfb8aa3b, v79
	v_exp_f32_e32 v80, v80
	v_exp_f32_e32 v81, v81
	v_add_f32_e32 v80, 1.0, v80
	v_add_f32_e32 v81, 1.0, v81
	v_rcp_f32_e32 v80, v80
	v_rcp_f32_e32 v81, v81
	s_nop 0
	v_pk_mul_f32 v[78:79], v[78:79], v[80:81]
	s_nop 0
	v_pk_mul_f32 v[72:73], v[72:73], v[78:79]
	v_mul_f32_e32 v78, 0xbfb8aa3b, v74
	v_mul_f32_e32 v79, 0xbfb8aa3b, v75
	v_exp_f32_e32 v78, v78
	v_exp_f32_e32 v79, v79
	v_add_f32_e32 v78, 1.0, v78
	v_add_f32_e32 v79, 1.0, v79
	v_rcp_f32_e32 v78, v78
	v_rcp_f32_e32 v79, v79
	s_nop 0
	v_pk_mul_f32 v[74:75], v[74:75], v[78:79]
	s_nop 0
	v_pk_mul_f32 v[74:75], v[66:67], v[74:75]
	v_pk_mul_f32 v[66:67], v[76:77], v[84:85] op_sel_hi:[1,0]
	s_nop 0
	v_mul_f32_e32 v76, 0xbfb8aa3b, v66
	v_mul_f32_e32 v77, 0xbfb8aa3b, v67
	v_exp_f32_e32 v76, v76
	v_exp_f32_e32 v77, v77
	v_add_f32_e32 v76, 1.0, v76
	v_add_f32_e32 v77, 1.0, v77
	v_rcp_f32_e32 v76, v76
	v_rcp_f32_e32 v77, v77
	s_nop 0
	v_pk_mul_f32 v[66:67], v[66:67], v[76:77]
	s_nop 0
	v_pk_mul_f32 v[76:77], v[68:69], v[66:67]
	v_cvt_pk_bf16_f32 v66, v70, v71
	v_mad_i64_i32 v[70:71], s[12:13], v82, s83, v[118:119]
	v_lshl_add_u64 v[70:71], v[70:71], 0, s[22:23]
	v_lshl_add_u64 v[70:71], v[70:71], 0, s[90:91]
	v_cvt_pk_bf16_f32 v67, v72, v73
	v_cvt_pk_bf16_f32 v68, v74, v75
	v_cvt_pk_bf16_f32 v69, v76, v77
	v_lshl_add_u64 v[70:71], v[70:71], 0, v[0:1]
	global_store_dwordx4 v[70:71], v[66:69], off
	s_nop 1
	v_add_u32_e32 v66, 0x80, v142
	v_ashrrev_i32_e32 v67, 31, v66
	s_waitcnt vmcnt(7)
	v_ffbh_u32_e32 v67, v211
	v_min_u32_e32 v67, 32, v67
	v_lshlrev_b64 v[68:69], v67, v[210:211]
	v_min_u32_e32 v68, 1, v68
	v_or_b32_e32 v68, v69, v68
	v_cvt_f32_u32_e32 v68, v68
	v_sub_u32_e32 v67, 32, v67
	v_ldexp_f32 v67, v68, v67
	v_mul_f32_e32 v67, 0x37800000, v67
	v_fmamk_f32 v67, v67, 0x3a800000, v195
	v_rsq_f32_e32 v68, v67
	s_nop 0
	v_pk_mul_f32 v[62:63], v[62:63], v[68:69] op_sel_hi:[1,0]
	s_nop 0
	v_mul_f32_e32 v67, 0xbfb8aa3b, v62
	v_exp_f32_e32 v67, v67
	v_pk_mul_f32 v[54:55], v[54:55], v[68:69] op_sel_hi:[1,0]
	v_pk_mul_f32 v[56:57], v[56:57], v[68:69] op_sel_hi:[1,0]
	v_pk_mul_f32 v[58:59], v[58:59], v[68:69] op_sel_hi:[1,0]
	v_add_f32_e32 v67, 1.0, v67
	v_rcp_f32_e32 v70, v67
	v_mul_f32_e32 v67, 0xbfb8aa3b, v63
	v_exp_f32_e32 v67, v67
	v_pk_mul_f32 v[50:51], v[50:51], v[68:69] op_sel_hi:[1,0]
	v_pk_mul_f32 v[52:53], v[52:53], v[68:69] op_sel_hi:[1,0]
	v_add_f32_e32 v67, 1.0, v67
	v_rcp_f32_e32 v71, v67
	s_nop 0
	v_pk_mul_f32 v[62:63], v[62:63], v[70:71]
	s_nop 0
	v_pk_mul_f32 v[54:55], v[54:55], v[62:63]
	v_pk_mul_f32 v[62:63], v[64:65], v[68:69] op_sel_hi:[1,0]
	s_nop 0
	v_mul_f32_e32 v64, 0xbfb8aa3b, v62
	v_mul_f32_e32 v65, 0xbfb8aa3b, v63
	v_exp_f32_e32 v64, v64
	v_exp_f32_e32 v65, v65
	v_add_f32_e32 v64, 1.0, v64
	v_add_f32_e32 v65, 1.0, v65
	v_rcp_f32_e32 v64, v64
	v_rcp_f32_e32 v65, v65
	s_nop 0
	v_pk_mul_f32 v[62:63], v[62:63], v[64:65]
	s_nop 0
	v_pk_mul_f32 v[56:57], v[56:57], v[62:63]
	v_mul_f32_e32 v62, 0xbfb8aa3b, v58
	v_mul_f32_e32 v63, 0xbfb8aa3b, v59
	v_exp_f32_e32 v62, v62
	v_exp_f32_e32 v63, v63
	v_add_f32_e32 v62, 1.0, v62
	v_add_f32_e32 v63, 1.0, v63
	v_rcp_f32_e32 v62, v62
	v_rcp_f32_e32 v63, v63
	s_nop 0
	v_pk_mul_f32 v[58:59], v[58:59], v[62:63]
	s_nop 0
	v_pk_mul_f32 v[58:59], v[50:51], v[58:59]
	v_pk_mul_f32 v[50:51], v[60:61], v[68:69] op_sel_hi:[1,0]
	s_nop 0
	v_mul_f32_e32 v60, 0xbfb8aa3b, v50
	v_mul_f32_e32 v61, 0xbfb8aa3b, v51
	v_exp_f32_e32 v60, v60
	v_exp_f32_e32 v61, v61
	v_add_f32_e32 v60, 1.0, v60
	v_add_f32_e32 v61, 1.0, v61
	v_rcp_f32_e32 v60, v60
	v_rcp_f32_e32 v61, v61
	s_nop 0
	v_pk_mul_f32 v[50:51], v[50:51], v[60:61]
	s_nop 0
	v_pk_mul_f32 v[60:61], v[52:53], v[50:51]
	v_cvt_pk_bf16_f32 v50, v54, v55
	v_mad_i64_i32 v[54:55], s[12:13], v66, s83, v[118:119]
	v_lshl_add_u64 v[54:55], v[54:55], 0, s[22:23]
	v_lshl_add_u64 v[54:55], v[54:55], 0, s[90:91]
	v_cvt_pk_bf16_f32 v51, v56, v57
	v_cvt_pk_bf16_f32 v52, v58, v59
	v_cvt_pk_bf16_f32 v53, v60, v61
	v_lshl_add_u64 v[54:55], v[54:55], 0, v[0:1]
	global_store_dwordx4 v[54:55], v[50:53], off
	s_nop 1
	v_add_u32_e32 v50, 0x90, v142
	v_ashrrev_i32_e32 v51, 31, v50
	s_waitcnt vmcnt(7)
	v_ffbh_u32_e32 v51, v213
	v_min_u32_e32 v51, 32, v51
	v_lshlrev_b64 v[52:53], v51, v[212:213]
	v_min_u32_e32 v52, 1, v52
	v_or_b32_e32 v52, v53, v52
	v_cvt_f32_u32_e32 v52, v52
	v_sub_u32_e32 v51, 32, v51
	v_ldexp_f32 v51, v52, v51
	v_mul_f32_e32 v51, 0x37800000, v51
	v_fmamk_f32 v51, v51, 0x3a800000, v195
	v_rsq_f32_e32 v52, v51
	s_nop 0
	v_pk_mul_f32 v[46:47], v[46:47], v[52:53] op_sel_hi:[1,0]
	s_nop 0
	v_mul_f32_e32 v51, 0xbfb8aa3b, v46
	v_exp_f32_e32 v51, v51
	v_pk_mul_f32 v[38:39], v[38:39], v[52:53] op_sel_hi:[1,0]
	v_pk_mul_f32 v[40:41], v[40:41], v[52:53] op_sel_hi:[1,0]
	v_pk_mul_f32 v[42:43], v[42:43], v[52:53] op_sel_hi:[1,0]
	v_add_f32_e32 v51, 1.0, v51
	v_rcp_f32_e32 v54, v51
	v_mul_f32_e32 v51, 0xbfb8aa3b, v47
	v_exp_f32_e32 v51, v51
	v_pk_mul_f32 v[34:35], v[34:35], v[52:53] op_sel_hi:[1,0]
	v_pk_mul_f32 v[36:37], v[36:37], v[52:53] op_sel_hi:[1,0]
	v_add_f32_e32 v51, 1.0, v51
	v_rcp_f32_e32 v55, v51
	s_nop 0
	v_pk_mul_f32 v[46:47], v[46:47], v[54:55]
	s_nop 0
	v_pk_mul_f32 v[38:39], v[38:39], v[46:47]
	v_pk_mul_f32 v[46:47], v[48:49], v[52:53] op_sel_hi:[1,0]
	s_nop 0
	v_mul_f32_e32 v48, 0xbfb8aa3b, v46
	v_mul_f32_e32 v49, 0xbfb8aa3b, v47
	v_exp_f32_e32 v48, v48
	v_exp_f32_e32 v49, v49
	v_add_f32_e32 v48, 1.0, v48
	v_add_f32_e32 v49, 1.0, v49
	v_rcp_f32_e32 v48, v48
	v_rcp_f32_e32 v49, v49
	s_nop 0
	v_pk_mul_f32 v[46:47], v[46:47], v[48:49]
	s_nop 0
	v_pk_mul_f32 v[40:41], v[40:41], v[46:47]
	v_mul_f32_e32 v46, 0xbfb8aa3b, v42
	v_mul_f32_e32 v47, 0xbfb8aa3b, v43
	v_exp_f32_e32 v46, v46
	v_exp_f32_e32 v47, v47
	v_add_f32_e32 v46, 1.0, v46
	v_add_f32_e32 v47, 1.0, v47
	v_rcp_f32_e32 v46, v46
	v_rcp_f32_e32 v47, v47
	s_nop 0
	v_pk_mul_f32 v[42:43], v[42:43], v[46:47]
	s_nop 0
	v_pk_mul_f32 v[42:43], v[34:35], v[42:43]
	v_pk_mul_f32 v[34:35], v[44:45], v[52:53] op_sel_hi:[1,0]
	s_nop 0
	v_mul_f32_e32 v44, 0xbfb8aa3b, v34
	v_mul_f32_e32 v45, 0xbfb8aa3b, v35
	v_exp_f32_e32 v44, v44
	v_exp_f32_e32 v45, v45
	v_add_f32_e32 v44, 1.0, v44
	v_add_f32_e32 v45, 1.0, v45
	v_rcp_f32_e32 v44, v44
	v_rcp_f32_e32 v45, v45
	s_nop 0
	v_pk_mul_f32 v[34:35], v[34:35], v[44:45]
	s_nop 0
	v_pk_mul_f32 v[44:45], v[36:37], v[34:35]
	v_cvt_pk_bf16_f32 v34, v38, v39
	v_mad_i64_i32 v[38:39], s[12:13], v50, s83, v[118:119]
	v_lshl_add_u64 v[38:39], v[38:39], 0, s[22:23]
	v_lshl_add_u64 v[38:39], v[38:39], 0, s[90:91]
	v_cvt_pk_bf16_f32 v35, v40, v41
	v_cvt_pk_bf16_f32 v36, v42, v43
	v_cvt_pk_bf16_f32 v37, v44, v45
	v_lshl_add_u64 v[38:39], v[38:39], 0, v[0:1]
	global_store_dwordx4 v[38:39], v[34:37], off
	s_nop 1
	v_add_u32_e32 v34, 0xa0, v142
	v_ashrrev_i32_e32 v35, 31, v34
	s_waitcnt vmcnt(7)
	v_ffbh_u32_e32 v35, v215
	v_min_u32_e32 v35, 32, v35
	v_lshlrev_b64 v[36:37], v35, v[214:215]
	v_min_u32_e32 v36, 1, v36
	v_or_b32_e32 v36, v37, v36
	v_cvt_f32_u32_e32 v36, v36
	v_sub_u32_e32 v35, 32, v35
	v_ldexp_f32 v35, v36, v35
	v_mul_f32_e32 v35, 0x37800000, v35
	v_fmamk_f32 v35, v35, 0x3a800000, v195
	v_rsq_f32_e32 v36, v35
	s_nop 0
	v_pk_mul_f32 v[30:31], v[30:31], v[36:37] op_sel_hi:[1,0]
	s_nop 0
	v_mul_f32_e32 v35, 0xbfb8aa3b, v30
	v_exp_f32_e32 v35, v35
	v_pk_mul_f32 v[22:23], v[22:23], v[36:37] op_sel_hi:[1,0]
	v_pk_mul_f32 v[24:25], v[24:25], v[36:37] op_sel_hi:[1,0]
	v_pk_mul_f32 v[26:27], v[26:27], v[36:37] op_sel_hi:[1,0]
	v_add_f32_e32 v35, 1.0, v35
	v_rcp_f32_e32 v38, v35
	v_mul_f32_e32 v35, 0xbfb8aa3b, v31
	v_exp_f32_e32 v35, v35
	v_pk_mul_f32 v[18:19], v[18:19], v[36:37] op_sel_hi:[1,0]
	v_pk_mul_f32 v[20:21], v[20:21], v[36:37] op_sel_hi:[1,0]
	v_add_f32_e32 v35, 1.0, v35
	v_rcp_f32_e32 v39, v35
	s_nop 0
	v_pk_mul_f32 v[30:31], v[30:31], v[38:39]
	s_nop 0
	v_pk_mul_f32 v[22:23], v[22:23], v[30:31]
	v_pk_mul_f32 v[30:31], v[32:33], v[36:37] op_sel_hi:[1,0]
	s_nop 0
	v_mul_f32_e32 v32, 0xbfb8aa3b, v30
	v_mul_f32_e32 v33, 0xbfb8aa3b, v31
	v_exp_f32_e32 v32, v32
	v_exp_f32_e32 v33, v33
	v_add_f32_e32 v32, 1.0, v32
	v_add_f32_e32 v33, 1.0, v33
	v_rcp_f32_e32 v32, v32
	v_rcp_f32_e32 v33, v33
	s_nop 0
	v_pk_mul_f32 v[30:31], v[30:31], v[32:33]
	s_nop 0
	v_pk_mul_f32 v[24:25], v[24:25], v[30:31]
	v_mul_f32_e32 v30, 0xbfb8aa3b, v26
	v_mul_f32_e32 v31, 0xbfb8aa3b, v27
	v_exp_f32_e32 v30, v30
	v_exp_f32_e32 v31, v31
	v_add_f32_e32 v30, 1.0, v30
	v_add_f32_e32 v31, 1.0, v31
	v_rcp_f32_e32 v30, v30
	v_rcp_f32_e32 v31, v31
	s_nop 0
	v_pk_mul_f32 v[26:27], v[26:27], v[30:31]
	s_nop 0
	v_pk_mul_f32 v[26:27], v[18:19], v[26:27]
	v_pk_mul_f32 v[18:19], v[28:29], v[36:37] op_sel_hi:[1,0]
	s_nop 0
	v_mul_f32_e32 v28, 0xbfb8aa3b, v18
	v_mul_f32_e32 v29, 0xbfb8aa3b, v19
	v_exp_f32_e32 v28, v28
	v_exp_f32_e32 v29, v29
	v_add_f32_e32 v28, 1.0, v28
	v_add_f32_e32 v29, 1.0, v29
	v_rcp_f32_e32 v28, v28
	v_rcp_f32_e32 v29, v29
	s_nop 0
	v_pk_mul_f32 v[18:19], v[18:19], v[28:29]
	s_nop 0
	v_pk_mul_f32 v[28:29], v[20:21], v[18:19]
	v_cvt_pk_bf16_f32 v18, v22, v23
	v_mad_i64_i32 v[22:23], s[12:13], v34, s83, v[118:119]
	v_lshl_add_u64 v[22:23], v[22:23], 0, s[22:23]
	v_lshl_add_u64 v[22:23], v[22:23], 0, s[90:91]
	v_cvt_pk_bf16_f32 v19, v24, v25
	v_cvt_pk_bf16_f32 v20, v26, v27
	v_cvt_pk_bf16_f32 v21, v28, v29
	v_lshl_add_u64 v[22:23], v[22:23], 0, v[0:1]
	global_store_dwordx4 v[22:23], v[18:21], off
	s_nop 1
	v_add_u32_e32 v18, 0xb0, v142
	v_ashrrev_i32_e32 v19, 31, v18
	s_waitcnt vmcnt(7)
	v_ffbh_u32_e32 v19, v217
	v_min_u32_e32 v19, 32, v19
	v_lshlrev_b64 v[20:21], v19, v[216:217]
	v_min_u32_e32 v20, 1, v20
	v_or_b32_e32 v20, v21, v20
	v_cvt_f32_u32_e32 v20, v20
	v_sub_u32_e32 v19, 32, v19
	v_ldexp_f32 v19, v20, v19
	v_mul_f32_e32 v19, 0x37800000, v19
	v_fmamk_f32 v19, v19, 0x3a800000, v195
	v_rsq_f32_e32 v20, v19
	s_nop 0
	v_pk_mul_f32 v[14:15], v[14:15], v[20:21] op_sel_hi:[1,0]
	s_nop 0
	v_mul_f32_e32 v19, 0xbfb8aa3b, v14
	v_exp_f32_e32 v19, v19
	v_pk_mul_f32 v[6:7], v[6:7], v[20:21] op_sel_hi:[1,0]
	v_pk_mul_f32 v[8:9], v[8:9], v[20:21] op_sel_hi:[1,0]
	v_pk_mul_f32 v[10:11], v[10:11], v[20:21] op_sel_hi:[1,0]
	v_add_f32_e32 v19, 1.0, v19
	v_rcp_f32_e32 v22, v19
	v_mul_f32_e32 v19, 0xbfb8aa3b, v15
	v_exp_f32_e32 v19, v19
	v_pk_mul_f32 v[2:3], v[2:3], v[20:21] op_sel_hi:[1,0]
	v_pk_mul_f32 v[4:5], v[4:5], v[20:21] op_sel_hi:[1,0]
	v_add_f32_e32 v19, 1.0, v19
	v_rcp_f32_e32 v23, v19
	s_nop 0
	v_pk_mul_f32 v[14:15], v[14:15], v[22:23]
	s_nop 0
	v_pk_mul_f32 v[6:7], v[6:7], v[14:15]
	v_pk_mul_f32 v[14:15], v[16:17], v[20:21] op_sel_hi:[1,0]
	s_nop 0
	v_mul_f32_e32 v16, 0xbfb8aa3b, v14
	v_mul_f32_e32 v17, 0xbfb8aa3b, v15
	v_exp_f32_e32 v16, v16
	v_exp_f32_e32 v17, v17
	v_add_f32_e32 v16, 1.0, v16
	v_add_f32_e32 v17, 1.0, v17
	v_rcp_f32_e32 v16, v16
	v_rcp_f32_e32 v17, v17
	s_nop 0
	v_pk_mul_f32 v[14:15], v[14:15], v[16:17]
	s_nop 0
	v_pk_mul_f32 v[8:9], v[8:9], v[14:15]
	v_mul_f32_e32 v14, 0xbfb8aa3b, v10
	v_mul_f32_e32 v15, 0xbfb8aa3b, v11
	v_exp_f32_e32 v14, v14
	v_exp_f32_e32 v15, v15
	v_add_f32_e32 v14, 1.0, v14
	v_add_f32_e32 v15, 1.0, v15
	v_rcp_f32_e32 v14, v14
	v_rcp_f32_e32 v15, v15
	s_nop 0
	v_pk_mul_f32 v[10:11], v[10:11], v[14:15]
	s_nop 0
	v_pk_mul_f32 v[10:11], v[2:3], v[10:11]
	v_pk_mul_f32 v[2:3], v[12:13], v[20:21] op_sel_hi:[1,0]
	s_nop 0
	v_mul_f32_e32 v12, 0xbfb8aa3b, v2
	v_mul_f32_e32 v13, 0xbfb8aa3b, v3
	v_exp_f32_e32 v12, v12
	v_exp_f32_e32 v13, v13
	v_add_f32_e32 v12, 1.0, v12
	v_add_f32_e32 v13, 1.0, v13
	v_rcp_f32_e32 v12, v12
	v_rcp_f32_e32 v13, v13
	s_nop 0
	v_pk_mul_f32 v[2:3], v[2:3], v[12:13]
	s_nop 0
	v_pk_mul_f32 v[12:13], v[4:5], v[2:3]
	v_cvt_pk_bf16_f32 v2, v6, v7
	v_mad_i64_i32 v[6:7], s[12:13], v18, s83, v[118:119]
	v_lshl_add_u64 v[6:7], v[6:7], 0, s[22:23]
	v_lshl_add_u64 v[6:7], v[6:7], 0, s[90:91]
	v_cvt_pk_bf16_f32 v3, v8, v9
	v_cvt_pk_bf16_f32 v4, v10, v11
	v_cvt_pk_bf16_f32 v5, v12, v13
	v_lshl_add_u64 v[6:7], v[6:7], 0, v[0:1]
	global_store_dwordx4 v[6:7], v[2:5], off
	s_mov_b64 s[22:23], -1
	s_cbranch_vccnz .LBB0_951
	s_andn2_b64 vcc, exec, s[6:7]
	s_cbranch_vccnz .LBB0_950
	s_barrier
	s_branch .LBB0_950
